# prep: fp4 table conversion as a hand-written software-pipelined loop, 4 rows in flight per wave, saddr loads/stores, DPP+permlane max reduction (bit-identical)
# speedup vs baseline: 1.0655x; 1.0015x over previous
.LBB0_29:
	v_and_b32_e32 v83, 63, v154
	v_lshlrev_b32_e32 v80, 6, v83
	v_lshlrev_b32_e32 v81, 3, v83
	v_mov_b32_e32 v82, 0
	v_lshrrev_b32_e32 v83, 6, v154
	s_mov_b32 s34, 0x40c00000
	s_lshl_b32 s100, s33, 2
	s_mov_b32 s101, 0x10000
	v_readfirstlane_b32 s35, v83
	s_mov_b32 s71, s2
.Luv_first:
	s_cmpk_ge_u32 s71, 0xa00
	s_cbranch_scc1 .Luv_first_ok
	s_add_u32 s71, s71, s33
	s_branch .Luv_first
.Luv_first_ok:
	s_sub_u32 s71, s71, 0xa00
	s_lshl_b32 s71, s71, 2
	s_add_u32 s98, s71, s35
	s_mov_b32 s99, s98
	s_min_u32 s32, s99, 0xffff
	s_lshr_b32 s71, s32, 15
	s_and_b32 s32, s32, 0x7fff
	s_lshl_b32 s71, s71, 1
	s_add_u32 s71, s71, 29
	v_readlane_b32 s96, v245, s71
	s_add_u32 s71, s71, 1
	v_readlane_b32 s97, v245, s71
	s_lshl_b32 s32, s32, 12
	s_nop 0
	s_add_u32 s96, s96, s32
	s_addc_u32 s97, s97, 0
	s_nop 0
	global_load_dwordx4 v[100:103], v80, s[96:97]
	global_load_dwordx4 v[104:107], v80, s[96:97] offset:16
	global_load_dwordx4 v[108:111], v80, s[96:97] offset:32
	global_load_dwordx4 v[112:115], v80, s[96:97] offset:48
	s_add_u32 s99, s99, s100
	s_min_u32 s32, s99, 0xffff
	s_lshr_b32 s71, s32, 15
	s_and_b32 s32, s32, 0x7fff
	s_lshl_b32 s71, s71, 1
	s_add_u32 s71, s71, 29
	v_readlane_b32 s96, v245, s71
	s_add_u32 s71, s71, 1
	v_readlane_b32 s97, v245, s71
	s_lshl_b32 s32, s32, 12
	s_nop 0
	s_add_u32 s96, s96, s32
	s_addc_u32 s97, s97, 0
	s_nop 0
	global_load_dwordx4 v[116:119], v80, s[96:97]
	global_load_dwordx4 v[120:123], v80, s[96:97] offset:16
	global_load_dwordx4 v[124:127], v80, s[96:97] offset:32
	global_load_dwordx4 v[128:131], v80, s[96:97] offset:48
	s_add_u32 s99, s99, s100
	s_min_u32 s32, s99, 0xffff
	s_lshr_b32 s71, s32, 15
	s_and_b32 s32, s32, 0x7fff
	s_lshl_b32 s71, s71, 1
	s_add_u32 s71, s71, 29
	v_readlane_b32 s96, v245, s71
	s_add_u32 s71, s71, 1
	v_readlane_b32 s97, v245, s71
	s_lshl_b32 s32, s32, 12
	s_nop 0
	s_add_u32 s96, s96, s32
	s_addc_u32 s97, s97, 0
	s_nop 0
	global_load_dwordx4 v[160:163], v80, s[96:97]
	global_load_dwordx4 v[164:167], v80, s[96:97] offset:16
	global_load_dwordx4 v[168:171], v80, s[96:97] offset:32
	global_load_dwordx4 v[172:175], v80, s[96:97] offset:48
	s_add_u32 s99, s99, s100
	s_min_u32 s32, s99, 0xffff
	s_lshr_b32 s71, s32, 15
	s_and_b32 s32, s32, 0x7fff
	s_lshl_b32 s71, s71, 1
	s_add_u32 s71, s71, 29
	v_readlane_b32 s96, v245, s71
	s_add_u32 s71, s71, 1
	v_readlane_b32 s97, v245, s71
	s_lshl_b32 s32, s32, 12
	s_nop 0
	s_add_u32 s96, s96, s32
	s_addc_u32 s97, s97, 0
	s_nop 0
	global_load_dwordx4 v[176:179], v80, s[96:97]
	global_load_dwordx4 v[180:183], v80, s[96:97] offset:16
	global_load_dwordx4 v[184:187], v80, s[96:97] offset:32
	global_load_dwordx4 v[188:191], v80, s[96:97] offset:48
	s_add_u32 s99, s99, s100
	s_cmp_ge_u32 s98, s101
	s_cbranch_scc1 .Luv_done
	s_waitcnt vmcnt(12)
	v_max3_f32 v84, |v100|, |v101|, 0
	v_max3_f32 v84, |v102|, |v103|, v84
	v_max3_f32 v84, |v104|, |v105|, v84
	v_max3_f32 v84, |v106|, |v107|, v84
	v_max3_f32 v84, |v108|, |v109|, v84
	v_max3_f32 v84, |v110|, |v111|, v84
	v_max3_f32 v84, |v112|, |v113|, v84
	v_max3_f32 v84, |v114|, |v115|, v84
	s_nop 1
	v_max_f32_dpp v84, v84, v84 quad_perm:[1,0,3,2] row_mask:0xf bank_mask:0xf
	s_nop 1
	v_max_f32_dpp v84, v84, v84 quad_perm:[2,3,0,1] row_mask:0xf bank_mask:0xf
	s_nop 1
	v_max_f32_dpp v84, v84, v84 row_half_mirror row_mask:0xf bank_mask:0xf
	s_nop 1
	v_max_f32_dpp v84, v84, v84 row_mirror row_mask:0xf bank_mask:0xf
	v_mov_b32_e32 v83, v84
	s_nop 1
	v_permlane16_swap_b32_e32 v84, v83
	v_max_f32_e32 v84, v84, v83
	v_mov_b32_e32 v83, v84
	s_nop 1
	v_permlane32_swap_b32_e32 v84, v83
	v_max_f32_e32 v84, v84, v83
	v_div_scale_f32 v90, s[96:97], v84, v84, s34
	v_rcp_f32_e32 v91, v90
	v_div_scale_f32 v92, vcc, s34, v84, s34
	v_fma_f32 v93, -v90, v91, 1.0
	v_fmac_f32_e32 v91, v93, v91
	v_mul_f32_e32 v93, v92, v91
	v_fma_f32 v94, -v90, v93, v92
	v_fmac_f32_e32 v93, v94, v91
	v_fma_f32 v92, -v90, v93, v92
	v_div_fmas_f32 v92, v92, v91, v93
	v_div_fixup_f32 v92, v92, v84, s34
	v_cmp_lt_f32_e32 vcc, 0, v84
	v_mov_b32_e32 v86, 0
	v_mov_b32_e32 v87, 0
	v_cndmask_b32_e32 v85, 1.0, v92, vcc
	v_mul_f32_e32 v100, v100, v85
	v_mul_f32_e32 v101, v101, v85
	v_mul_f32_e32 v102, v102, v85
	v_mul_f32_e32 v103, v103, v85
	v_mul_f32_e32 v104, v104, v85
	v_mul_f32_e32 v105, v105, v85
	v_mul_f32_e32 v106, v106, v85
	v_mul_f32_e32 v107, v107, v85
	v_mul_f32_e32 v108, v108, v85
	v_mul_f32_e32 v109, v109, v85
	v_mul_f32_e32 v110, v110, v85
	v_mul_f32_e32 v111, v111, v85
	v_mul_f32_e32 v112, v112, v85
	v_mul_f32_e32 v113, v113, v85
	v_mul_f32_e32 v114, v114, v85
	v_mul_f32_e32 v115, v115, v85
	v_cvt_scalef32_pk_fp4_f32 v86, v100, v101, 1.0
	v_cvt_scalef32_pk_fp4_f32 v87, v108, v109, 1.0
	v_cvt_scalef32_pk_fp4_f32 v86, v102, v103, 1.0 op_sel:[0,0,1,0]
	v_cvt_scalef32_pk_fp4_f32 v87, v110, v111, 1.0 op_sel:[0,0,1,0]
	v_cvt_scalef32_pk_fp4_f32 v86, v104, v105, 1.0 op_sel:[0,0,0,1]
	v_cvt_scalef32_pk_fp4_f32 v87, v112, v113, 1.0 op_sel:[0,0,0,1]
	v_cvt_scalef32_pk_fp4_f32 v86, v106, v107, 1.0 op_sel:[0,0,1,1]
	v_cvt_scalef32_pk_fp4_f32 v87, v114, v115, 1.0 op_sel:[0,0,1,1]
	v_mul_f32_e32 v88, 0x3e2aaaab, v84
	s_lshr_b32 s71, s98, 15
	s_and_b32 s32, s98, 0x7fff
	s_lshl_b32 s71, s71, 1
	s_add_u32 s35, s71, 45
	v_readlane_b32 s96, v245, s35
	s_add_u32 s35, s35, 1
	v_readlane_b32 s97, v245, s35
	s_lshl_b32 s35, s32, 9
	s_nop 0
	s_add_u32 s96, s96, s35
	s_addc_u32 s97, s97, 0
	s_nop 0
	global_store_dwordx2 v81, v[86:87], s[96:97]
	s_add_u32 s35, s71, 53
	v_readlane_b32 s96, v245, s35
	s_add_u32 s35, s35, 1
	v_readlane_b32 s97, v245, s35
	s_lshl_b32 s35, s32, 2
	s_nop 0
	s_add_u32 s96, s96, s35
	s_addc_u32 s97, s97, 0
	s_mov_b64 exec, 1
	global_store_dword v82, v88, s[96:97]
	s_mov_b64 exec, -1
	s_add_u32 s98, s98, s100
	s_min_u32 s32, s99, 0xffff
	s_lshr_b32 s71, s32, 15
	s_and_b32 s32, s32, 0x7fff
	s_lshl_b32 s71, s71, 1
	s_add_u32 s71, s71, 29
	v_readlane_b32 s96, v245, s71
	s_add_u32 s71, s71, 1
	v_readlane_b32 s97, v245, s71
	s_lshl_b32 s32, s32, 12
	s_nop 0
	s_add_u32 s96, s96, s32
	s_addc_u32 s97, s97, 0
	s_nop 0
	global_load_dwordx4 v[100:103], v80, s[96:97]
	global_load_dwordx4 v[104:107], v80, s[96:97] offset:16
	global_load_dwordx4 v[108:111], v80, s[96:97] offset:32
	global_load_dwordx4 v[112:115], v80, s[96:97] offset:48
	s_add_u32 s99, s99, s100
	s_cmp_ge_u32 s98, s101
	s_cbranch_scc1 .Luv_done
	s_waitcnt vmcnt(14)
	v_max3_f32 v84, |v116|, |v117|, 0
	v_max3_f32 v84, |v118|, |v119|, v84
	v_max3_f32 v84, |v120|, |v121|, v84
	v_max3_f32 v84, |v122|, |v123|, v84
	v_max3_f32 v84, |v124|, |v125|, v84
	v_max3_f32 v84, |v126|, |v127|, v84
	v_max3_f32 v84, |v128|, |v129|, v84
	v_max3_f32 v84, |v130|, |v131|, v84
	s_nop 1
	v_max_f32_dpp v84, v84, v84 quad_perm:[1,0,3,2] row_mask:0xf bank_mask:0xf
	s_nop 1
	v_max_f32_dpp v84, v84, v84 quad_perm:[2,3,0,1] row_mask:0xf bank_mask:0xf
	s_nop 1
	v_max_f32_dpp v84, v84, v84 row_half_mirror row_mask:0xf bank_mask:0xf
	s_nop 1
	v_max_f32_dpp v84, v84, v84 row_mirror row_mask:0xf bank_mask:0xf
	v_mov_b32_e32 v83, v84
	s_nop 1
	v_permlane16_swap_b32_e32 v84, v83
	v_max_f32_e32 v84, v84, v83
	v_mov_b32_e32 v83, v84
	s_nop 1
	v_permlane32_swap_b32_e32 v84, v83
	v_max_f32_e32 v84, v84, v83
	v_div_scale_f32 v90, s[96:97], v84, v84, s34
	v_rcp_f32_e32 v91, v90
	v_div_scale_f32 v92, vcc, s34, v84, s34
	v_fma_f32 v93, -v90, v91, 1.0
	v_fmac_f32_e32 v91, v93, v91
	v_mul_f32_e32 v93, v92, v91
	v_fma_f32 v94, -v90, v93, v92
	v_fmac_f32_e32 v93, v94, v91
	v_fma_f32 v92, -v90, v93, v92
	v_div_fmas_f32 v92, v92, v91, v93
	v_div_fixup_f32 v92, v92, v84, s34
	v_cmp_lt_f32_e32 vcc, 0, v84
	v_mov_b32_e32 v86, 0
	v_mov_b32_e32 v87, 0
	v_cndmask_b32_e32 v85, 1.0, v92, vcc
	v_mul_f32_e32 v116, v116, v85
	v_mul_f32_e32 v117, v117, v85
	v_mul_f32_e32 v118, v118, v85
	v_mul_f32_e32 v119, v119, v85
	v_mul_f32_e32 v120, v120, v85
	v_mul_f32_e32 v121, v121, v85
	v_mul_f32_e32 v122, v122, v85
	v_mul_f32_e32 v123, v123, v85
	v_mul_f32_e32 v124, v124, v85
	v_mul_f32_e32 v125, v125, v85
	v_mul_f32_e32 v126, v126, v85
	v_mul_f32_e32 v127, v127, v85
	v_mul_f32_e32 v128, v128, v85
	v_mul_f32_e32 v129, v129, v85
	v_mul_f32_e32 v130, v130, v85
	v_mul_f32_e32 v131, v131, v85
	v_cvt_scalef32_pk_fp4_f32 v86, v116, v117, 1.0
	v_cvt_scalef32_pk_fp4_f32 v87, v124, v125, 1.0
	v_cvt_scalef32_pk_fp4_f32 v86, v118, v119, 1.0 op_sel:[0,0,1,0]
	v_cvt_scalef32_pk_fp4_f32 v87, v126, v127, 1.0 op_sel:[0,0,1,0]
	v_cvt_scalef32_pk_fp4_f32 v86, v120, v121, 1.0 op_sel:[0,0,0,1]
	v_cvt_scalef32_pk_fp4_f32 v87, v128, v129, 1.0 op_sel:[0,0,0,1]
	v_cvt_scalef32_pk_fp4_f32 v86, v122, v123, 1.0 op_sel:[0,0,1,1]
	v_cvt_scalef32_pk_fp4_f32 v87, v130, v131, 1.0 op_sel:[0,0,1,1]
	v_mul_f32_e32 v88, 0x3e2aaaab, v84
	s_lshr_b32 s71, s98, 15
	s_and_b32 s32, s98, 0x7fff
	s_lshl_b32 s71, s71, 1
	s_add_u32 s35, s71, 45
	v_readlane_b32 s96, v245, s35
	s_add_u32 s35, s35, 1
	v_readlane_b32 s97, v245, s35
	s_lshl_b32 s35, s32, 9
	s_nop 0
	s_add_u32 s96, s96, s35
	s_addc_u32 s97, s97, 0
	s_nop 0
	global_store_dwordx2 v81, v[86:87], s[96:97]
	s_add_u32 s35, s71, 53
	v_readlane_b32 s96, v245, s35
	s_add_u32 s35, s35, 1
	v_readlane_b32 s97, v245, s35
	s_lshl_b32 s35, s32, 2
	s_nop 0
	s_add_u32 s96, s96, s35
	s_addc_u32 s97, s97, 0
	s_mov_b64 exec, 1
	global_store_dword v82, v88, s[96:97]
	s_mov_b64 exec, -1
	s_add_u32 s98, s98, s100
	s_min_u32 s32, s99, 0xffff
	s_lshr_b32 s71, s32, 15
	s_and_b32 s32, s32, 0x7fff
	s_lshl_b32 s71, s71, 1
	s_add_u32 s71, s71, 29
	v_readlane_b32 s96, v245, s71
	s_add_u32 s71, s71, 1
	v_readlane_b32 s97, v245, s71
	s_lshl_b32 s32, s32, 12
	s_nop 0
	s_add_u32 s96, s96, s32
	s_addc_u32 s97, s97, 0
	s_nop 0
	global_load_dwordx4 v[116:119], v80, s[96:97]
	global_load_dwordx4 v[120:123], v80, s[96:97] offset:16
	global_load_dwordx4 v[124:127], v80, s[96:97] offset:32
	global_load_dwordx4 v[128:131], v80, s[96:97] offset:48
	s_add_u32 s99, s99, s100
	s_cmp_ge_u32 s98, s101
	s_cbranch_scc1 .Luv_done
	s_waitcnt vmcnt(16)
	v_max3_f32 v84, |v160|, |v161|, 0
	v_max3_f32 v84, |v162|, |v163|, v84
	v_max3_f32 v84, |v164|, |v165|, v84
	v_max3_f32 v84, |v166|, |v167|, v84
	v_max3_f32 v84, |v168|, |v169|, v84
	v_max3_f32 v84, |v170|, |v171|, v84
	v_max3_f32 v84, |v172|, |v173|, v84
	v_max3_f32 v84, |v174|, |v175|, v84
	s_nop 1
	v_max_f32_dpp v84, v84, v84 quad_perm:[1,0,3,2] row_mask:0xf bank_mask:0xf
	s_nop 1
	v_max_f32_dpp v84, v84, v84 quad_perm:[2,3,0,1] row_mask:0xf bank_mask:0xf
	s_nop 1
	v_max_f32_dpp v84, v84, v84 row_half_mirror row_mask:0xf bank_mask:0xf
	s_nop 1
	v_max_f32_dpp v84, v84, v84 row_mirror row_mask:0xf bank_mask:0xf
	v_mov_b32_e32 v83, v84
	s_nop 1
	v_permlane16_swap_b32_e32 v84, v83
	v_max_f32_e32 v84, v84, v83
	v_mov_b32_e32 v83, v84
	s_nop 1
	v_permlane32_swap_b32_e32 v84, v83
	v_max_f32_e32 v84, v84, v83
	v_div_scale_f32 v90, s[96:97], v84, v84, s34
	v_rcp_f32_e32 v91, v90
	v_div_scale_f32 v92, vcc, s34, v84, s34
	v_fma_f32 v93, -v90, v91, 1.0
	v_fmac_f32_e32 v91, v93, v91
	v_mul_f32_e32 v93, v92, v91
	v_fma_f32 v94, -v90, v93, v92
	v_fmac_f32_e32 v93, v94, v91
	v_fma_f32 v92, -v90, v93, v92
	v_div_fmas_f32 v92, v92, v91, v93
	v_div_fixup_f32 v92, v92, v84, s34
	v_cmp_lt_f32_e32 vcc, 0, v84
	v_mov_b32_e32 v86, 0
	v_mov_b32_e32 v87, 0
	v_cndmask_b32_e32 v85, 1.0, v92, vcc
	v_mul_f32_e32 v160, v160, v85
	v_mul_f32_e32 v161, v161, v85
	v_mul_f32_e32 v162, v162, v85
	v_mul_f32_e32 v163, v163, v85
	v_mul_f32_e32 v164, v164, v85
	v_mul_f32_e32 v165, v165, v85
	v_mul_f32_e32 v166, v166, v85
	v_mul_f32_e32 v167, v167, v85
	v_mul_f32_e32 v168, v168, v85
	v_mul_f32_e32 v169, v169, v85
	v_mul_f32_e32 v170, v170, v85
	v_mul_f32_e32 v171, v171, v85
	v_mul_f32_e32 v172, v172, v85
	v_mul_f32_e32 v173, v173, v85
	v_mul_f32_e32 v174, v174, v85
	v_mul_f32_e32 v175, v175, v85
	v_cvt_scalef32_pk_fp4_f32 v86, v160, v161, 1.0
	v_cvt_scalef32_pk_fp4_f32 v87, v168, v169, 1.0
	v_cvt_scalef32_pk_fp4_f32 v86, v162, v163, 1.0 op_sel:[0,0,1,0]
	v_cvt_scalef32_pk_fp4_f32 v87, v170, v171, 1.0 op_sel:[0,0,1,0]
	v_cvt_scalef32_pk_fp4_f32 v86, v164, v165, 1.0 op_sel:[0,0,0,1]
	v_cvt_scalef32_pk_fp4_f32 v87, v172, v173, 1.0 op_sel:[0,0,0,1]
	v_cvt_scalef32_pk_fp4_f32 v86, v166, v167, 1.0 op_sel:[0,0,1,1]
	v_cvt_scalef32_pk_fp4_f32 v87, v174, v175, 1.0 op_sel:[0,0,1,1]
	v_mul_f32_e32 v88, 0x3e2aaaab, v84
	s_lshr_b32 s71, s98, 15
	s_and_b32 s32, s98, 0x7fff
	s_lshl_b32 s71, s71, 1
	s_add_u32 s35, s71, 45
	v_readlane_b32 s96, v245, s35
	s_add_u32 s35, s35, 1
	v_readlane_b32 s97, v245, s35
	s_lshl_b32 s35, s32, 9
	s_nop 0
	s_add_u32 s96, s96, s35
	s_addc_u32 s97, s97, 0
	s_nop 0
	global_store_dwordx2 v81, v[86:87], s[96:97]
	s_add_u32 s35, s71, 53
	v_readlane_b32 s96, v245, s35
	s_add_u32 s35, s35, 1
	v_readlane_b32 s97, v245, s35
	s_lshl_b32 s35, s32, 2
	s_nop 0
	s_add_u32 s96, s96, s35
	s_addc_u32 s97, s97, 0
	s_mov_b64 exec, 1
	global_store_dword v82, v88, s[96:97]
	s_mov_b64 exec, -1
	s_add_u32 s98, s98, s100
	s_min_u32 s32, s99, 0xffff
	s_lshr_b32 s71, s32, 15
	s_and_b32 s32, s32, 0x7fff
	s_lshl_b32 s71, s71, 1
	s_add_u32 s71, s71, 29
	v_readlane_b32 s96, v245, s71
	s_add_u32 s71, s71, 1
	v_readlane_b32 s97, v245, s71
	s_lshl_b32 s32, s32, 12
	s_nop 0
	s_add_u32 s96, s96, s32
	s_addc_u32 s97, s97, 0
	s_nop 0
	global_load_dwordx4 v[160:163], v80, s[96:97]
	global_load_dwordx4 v[164:167], v80, s[96:97] offset:16
	global_load_dwordx4 v[168:171], v80, s[96:97] offset:32
	global_load_dwordx4 v[172:175], v80, s[96:97] offset:48
	s_add_u32 s99, s99, s100
	s_cmp_ge_u32 s98, s101
	s_cbranch_scc1 .Luv_done
	s_waitcnt vmcnt(18)
	v_max3_f32 v84, |v176|, |v177|, 0
	v_max3_f32 v84, |v178|, |v179|, v84
	v_max3_f32 v84, |v180|, |v181|, v84
	v_max3_f32 v84, |v182|, |v183|, v84
	v_max3_f32 v84, |v184|, |v185|, v84
	v_max3_f32 v84, |v186|, |v187|, v84
	v_max3_f32 v84, |v188|, |v189|, v84
	v_max3_f32 v84, |v190|, |v191|, v84
	s_nop 1
	v_max_f32_dpp v84, v84, v84 quad_perm:[1,0,3,2] row_mask:0xf bank_mask:0xf
	s_nop 1
	v_max_f32_dpp v84, v84, v84 quad_perm:[2,3,0,1] row_mask:0xf bank_mask:0xf
	s_nop 1
	v_max_f32_dpp v84, v84, v84 row_half_mirror row_mask:0xf bank_mask:0xf
	s_nop 1
	v_max_f32_dpp v84, v84, v84 row_mirror row_mask:0xf bank_mask:0xf
	v_mov_b32_e32 v83, v84
	s_nop 1
	v_permlane16_swap_b32_e32 v84, v83
	v_max_f32_e32 v84, v84, v83
	v_mov_b32_e32 v83, v84
	s_nop 1
	v_permlane32_swap_b32_e32 v84, v83
	v_max_f32_e32 v84, v84, v83
	v_div_scale_f32 v90, s[96:97], v84, v84, s34
	v_rcp_f32_e32 v91, v90
	v_div_scale_f32 v92, vcc, s34, v84, s34
	v_fma_f32 v93, -v90, v91, 1.0
	v_fmac_f32_e32 v91, v93, v91
	v_mul_f32_e32 v93, v92, v91
	v_fma_f32 v94, -v90, v93, v92
	v_fmac_f32_e32 v93, v94, v91
	v_fma_f32 v92, -v90, v93, v92
	v_div_fmas_f32 v92, v92, v91, v93
	v_div_fixup_f32 v92, v92, v84, s34
	v_cmp_lt_f32_e32 vcc, 0, v84
	v_mov_b32_e32 v86, 0
	v_mov_b32_e32 v87, 0
	v_cndmask_b32_e32 v85, 1.0, v92, vcc
	v_mul_f32_e32 v176, v176, v85
	v_mul_f32_e32 v177, v177, v85
	v_mul_f32_e32 v178, v178, v85
	v_mul_f32_e32 v179, v179, v85
	v_mul_f32_e32 v180, v180, v85
	v_mul_f32_e32 v181, v181, v85
	v_mul_f32_e32 v182, v182, v85
	v_mul_f32_e32 v183, v183, v85
	v_mul_f32_e32 v184, v184, v85
	v_mul_f32_e32 v185, v185, v85
	v_mul_f32_e32 v186, v186, v85
	v_mul_f32_e32 v187, v187, v85
	v_mul_f32_e32 v188, v188, v85
	v_mul_f32_e32 v189, v189, v85
	v_mul_f32_e32 v190, v190, v85
	v_mul_f32_e32 v191, v191, v85
	v_cvt_scalef32_pk_fp4_f32 v86, v176, v177, 1.0
	v_cvt_scalef32_pk_fp4_f32 v87, v184, v185, 1.0
	v_cvt_scalef32_pk_fp4_f32 v86, v178, v179, 1.0 op_sel:[0,0,1,0]
	v_cvt_scalef32_pk_fp4_f32 v87, v186, v187, 1.0 op_sel:[0,0,1,0]
	v_cvt_scalef32_pk_fp4_f32 v86, v180, v181, 1.0 op_sel:[0,0,0,1]
	v_cvt_scalef32_pk_fp4_f32 v87, v188, v189, 1.0 op_sel:[0,0,0,1]
	v_cvt_scalef32_pk_fp4_f32 v86, v182, v183, 1.0 op_sel:[0,0,1,1]
	v_cvt_scalef32_pk_fp4_f32 v87, v190, v191, 1.0 op_sel:[0,0,1,1]
	v_mul_f32_e32 v88, 0x3e2aaaab, v84
	s_lshr_b32 s71, s98, 15
	s_and_b32 s32, s98, 0x7fff
	s_lshl_b32 s71, s71, 1
	s_add_u32 s35, s71, 45
	v_readlane_b32 s96, v245, s35
	s_add_u32 s35, s35, 1
	v_readlane_b32 s97, v245, s35
	s_lshl_b32 s35, s32, 9
	s_nop 0
	s_add_u32 s96, s96, s35
	s_addc_u32 s97, s97, 0
	s_nop 0
	global_store_dwordx2 v81, v[86:87], s[96:97]
	s_add_u32 s35, s71, 53
	v_readlane_b32 s96, v245, s35
	s_add_u32 s35, s35, 1
	v_readlane_b32 s97, v245, s35
	s_lshl_b32 s35, s32, 2
	s_nop 0
	s_add_u32 s96, s96, s35
	s_addc_u32 s97, s97, 0
	s_mov_b64 exec, 1
	global_store_dword v82, v88, s[96:97]
	s_mov_b64 exec, -1
	s_add_u32 s98, s98, s100
	s_min_u32 s32, s99, 0xffff
	s_lshr_b32 s71, s32, 15
	s_and_b32 s32, s32, 0x7fff
	s_lshl_b32 s71, s71, 1
	s_add_u32 s71, s71, 29
	v_readlane_b32 s96, v245, s71
	s_add_u32 s71, s71, 1
	v_readlane_b32 s97, v245, s71
	s_lshl_b32 s32, s32, 12
	s_nop 0
	s_add_u32 s96, s96, s32
	s_addc_u32 s97, s97, 0
	s_nop 0
	global_load_dwordx4 v[176:179], v80, s[96:97]
	global_load_dwordx4 v[180:183], v80, s[96:97] offset:16
	global_load_dwordx4 v[184:187], v80, s[96:97] offset:32
	global_load_dwordx4 v[188:191], v80, s[96:97] offset:48
	s_add_u32 s99, s99, s100
.Luv_loop:
	s_cmp_ge_u32 s98, s101
	s_cbranch_scc1 .Luv_done
	s_waitcnt vmcnt(18)
	v_max3_f32 v84, |v100|, |v101|, 0
	v_max3_f32 v84, |v102|, |v103|, v84
	v_max3_f32 v84, |v104|, |v105|, v84
	v_max3_f32 v84, |v106|, |v107|, v84
	v_max3_f32 v84, |v108|, |v109|, v84
	v_max3_f32 v84, |v110|, |v111|, v84
	v_max3_f32 v84, |v112|, |v113|, v84
	v_max3_f32 v84, |v114|, |v115|, v84
	s_nop 1
	v_max_f32_dpp v84, v84, v84 quad_perm:[1,0,3,2] row_mask:0xf bank_mask:0xf
	s_nop 1
	v_max_f32_dpp v84, v84, v84 quad_perm:[2,3,0,1] row_mask:0xf bank_mask:0xf
	s_nop 1
	v_max_f32_dpp v84, v84, v84 row_half_mirror row_mask:0xf bank_mask:0xf
	s_nop 1
	v_max_f32_dpp v84, v84, v84 row_mirror row_mask:0xf bank_mask:0xf
	v_mov_b32_e32 v83, v84
	s_nop 1
	v_permlane16_swap_b32_e32 v84, v83
	v_max_f32_e32 v84, v84, v83
	v_mov_b32_e32 v83, v84
	s_nop 1
	v_permlane32_swap_b32_e32 v84, v83
	v_max_f32_e32 v84, v84, v83
	v_div_scale_f32 v90, s[96:97], v84, v84, s34
	v_rcp_f32_e32 v91, v90
	v_div_scale_f32 v92, vcc, s34, v84, s34
	v_fma_f32 v93, -v90, v91, 1.0
	v_fmac_f32_e32 v91, v93, v91
	v_mul_f32_e32 v93, v92, v91
	v_fma_f32 v94, -v90, v93, v92
	v_fmac_f32_e32 v93, v94, v91
	v_fma_f32 v92, -v90, v93, v92
	v_div_fmas_f32 v92, v92, v91, v93
	v_div_fixup_f32 v92, v92, v84, s34
	v_cmp_lt_f32_e32 vcc, 0, v84
	v_mov_b32_e32 v86, 0
	v_mov_b32_e32 v87, 0
	v_cndmask_b32_e32 v85, 1.0, v92, vcc
	v_mul_f32_e32 v100, v100, v85
	v_mul_f32_e32 v101, v101, v85
	v_mul_f32_e32 v102, v102, v85
	v_mul_f32_e32 v103, v103, v85
	v_mul_f32_e32 v104, v104, v85
	v_mul_f32_e32 v105, v105, v85
	v_mul_f32_e32 v106, v106, v85
	v_mul_f32_e32 v107, v107, v85
	v_mul_f32_e32 v108, v108, v85
	v_mul_f32_e32 v109, v109, v85
	v_mul_f32_e32 v110, v110, v85
	v_mul_f32_e32 v111, v111, v85
	v_mul_f32_e32 v112, v112, v85
	v_mul_f32_e32 v113, v113, v85
	v_mul_f32_e32 v114, v114, v85
	v_mul_f32_e32 v115, v115, v85
	v_cvt_scalef32_pk_fp4_f32 v86, v100, v101, 1.0
	v_cvt_scalef32_pk_fp4_f32 v87, v108, v109, 1.0
	v_cvt_scalef32_pk_fp4_f32 v86, v102, v103, 1.0 op_sel:[0,0,1,0]
	v_cvt_scalef32_pk_fp4_f32 v87, v110, v111, 1.0 op_sel:[0,0,1,0]
	v_cvt_scalef32_pk_fp4_f32 v86, v104, v105, 1.0 op_sel:[0,0,0,1]
	v_cvt_scalef32_pk_fp4_f32 v87, v112, v113, 1.0 op_sel:[0,0,0,1]
	v_cvt_scalef32_pk_fp4_f32 v86, v106, v107, 1.0 op_sel:[0,0,1,1]
	v_cvt_scalef32_pk_fp4_f32 v87, v114, v115, 1.0 op_sel:[0,0,1,1]
	v_mul_f32_e32 v88, 0x3e2aaaab, v84
	s_lshr_b32 s71, s98, 15
	s_and_b32 s32, s98, 0x7fff
	s_lshl_b32 s71, s71, 1
	s_add_u32 s35, s71, 45
	v_readlane_b32 s96, v245, s35
	s_add_u32 s35, s35, 1
	v_readlane_b32 s97, v245, s35
	s_lshl_b32 s35, s32, 9
	s_nop 0
	s_add_u32 s96, s96, s35
	s_addc_u32 s97, s97, 0
	s_nop 0
	global_store_dwordx2 v81, v[86:87], s[96:97]
	s_add_u32 s35, s71, 53
	v_readlane_b32 s96, v245, s35
	s_add_u32 s35, s35, 1
	v_readlane_b32 s97, v245, s35
	s_lshl_b32 s35, s32, 2
	s_nop 0
	s_add_u32 s96, s96, s35
	s_addc_u32 s97, s97, 0
	s_mov_b64 exec, 1
	global_store_dword v82, v88, s[96:97]
	s_mov_b64 exec, -1
	s_add_u32 s98, s98, s100
	s_min_u32 s32, s99, 0xffff
	s_lshr_b32 s71, s32, 15
	s_and_b32 s32, s32, 0x7fff
	s_lshl_b32 s71, s71, 1
	s_add_u32 s71, s71, 29
	v_readlane_b32 s96, v245, s71
	s_add_u32 s71, s71, 1
	v_readlane_b32 s97, v245, s71
	s_lshl_b32 s32, s32, 12
	s_nop 0
	s_add_u32 s96, s96, s32
	s_addc_u32 s97, s97, 0
	s_nop 0
	global_load_dwordx4 v[100:103], v80, s[96:97]
	global_load_dwordx4 v[104:107], v80, s[96:97] offset:16
	global_load_dwordx4 v[108:111], v80, s[96:97] offset:32
	global_load_dwordx4 v[112:115], v80, s[96:97] offset:48
	s_add_u32 s99, s99, s100
	s_cmp_ge_u32 s98, s101
	s_cbranch_scc1 .Luv_done
	s_waitcnt vmcnt(18)
	v_max3_f32 v84, |v116|, |v117|, 0
	v_max3_f32 v84, |v118|, |v119|, v84
	v_max3_f32 v84, |v120|, |v121|, v84
	v_max3_f32 v84, |v122|, |v123|, v84
	v_max3_f32 v84, |v124|, |v125|, v84
	v_max3_f32 v84, |v126|, |v127|, v84
	v_max3_f32 v84, |v128|, |v129|, v84
	v_max3_f32 v84, |v130|, |v131|, v84
	s_nop 1
	v_max_f32_dpp v84, v84, v84 quad_perm:[1,0,3,2] row_mask:0xf bank_mask:0xf
	s_nop 1
	v_max_f32_dpp v84, v84, v84 quad_perm:[2,3,0,1] row_mask:0xf bank_mask:0xf
	s_nop 1
	v_max_f32_dpp v84, v84, v84 row_half_mirror row_mask:0xf bank_mask:0xf
	s_nop 1
	v_max_f32_dpp v84, v84, v84 row_mirror row_mask:0xf bank_mask:0xf
	v_mov_b32_e32 v83, v84
	s_nop 1
	v_permlane16_swap_b32_e32 v84, v83
	v_max_f32_e32 v84, v84, v83
	v_mov_b32_e32 v83, v84
	s_nop 1
	v_permlane32_swap_b32_e32 v84, v83
	v_max_f32_e32 v84, v84, v83
	v_div_scale_f32 v90, s[96:97], v84, v84, s34
	v_rcp_f32_e32 v91, v90
	v_div_scale_f32 v92, vcc, s34, v84, s34
	v_fma_f32 v93, -v90, v91, 1.0
	v_fmac_f32_e32 v91, v93, v91
	v_mul_f32_e32 v93, v92, v91
	v_fma_f32 v94, -v90, v93, v92
	v_fmac_f32_e32 v93, v94, v91
	v_fma_f32 v92, -v90, v93, v92
	v_div_fmas_f32 v92, v92, v91, v93
	v_div_fixup_f32 v92, v92, v84, s34
	v_cmp_lt_f32_e32 vcc, 0, v84
	v_mov_b32_e32 v86, 0
	v_mov_b32_e32 v87, 0
	v_cndmask_b32_e32 v85, 1.0, v92, vcc
	v_mul_f32_e32 v116, v116, v85
	v_mul_f32_e32 v117, v117, v85
	v_mul_f32_e32 v118, v118, v85
	v_mul_f32_e32 v119, v119, v85
	v_mul_f32_e32 v120, v120, v85
	v_mul_f32_e32 v121, v121, v85
	v_mul_f32_e32 v122, v122, v85
	v_mul_f32_e32 v123, v123, v85
	v_mul_f32_e32 v124, v124, v85
	v_mul_f32_e32 v125, v125, v85
	v_mul_f32_e32 v126, v126, v85
	v_mul_f32_e32 v127, v127, v85
	v_mul_f32_e32 v128, v128, v85
	v_mul_f32_e32 v129, v129, v85
	v_mul_f32_e32 v130, v130, v85
	v_mul_f32_e32 v131, v131, v85
	v_cvt_scalef32_pk_fp4_f32 v86, v116, v117, 1.0
	v_cvt_scalef32_pk_fp4_f32 v87, v124, v125, 1.0
	v_cvt_scalef32_pk_fp4_f32 v86, v118, v119, 1.0 op_sel:[0,0,1,0]
	v_cvt_scalef32_pk_fp4_f32 v87, v126, v127, 1.0 op_sel:[0,0,1,0]
	v_cvt_scalef32_pk_fp4_f32 v86, v120, v121, 1.0 op_sel:[0,0,0,1]
	v_cvt_scalef32_pk_fp4_f32 v87, v128, v129, 1.0 op_sel:[0,0,0,1]
	v_cvt_scalef32_pk_fp4_f32 v86, v122, v123, 1.0 op_sel:[0,0,1,1]
	v_cvt_scalef32_pk_fp4_f32 v87, v130, v131, 1.0 op_sel:[0,0,1,1]
	v_mul_f32_e32 v88, 0x3e2aaaab, v84
	s_lshr_b32 s71, s98, 15
	s_and_b32 s32, s98, 0x7fff
	s_lshl_b32 s71, s71, 1
	s_add_u32 s35, s71, 45
	v_readlane_b32 s96, v245, s35
	s_add_u32 s35, s35, 1
	v_readlane_b32 s97, v245, s35
	s_lshl_b32 s35, s32, 9
	s_nop 0
	s_add_u32 s96, s96, s35
	s_addc_u32 s97, s97, 0
	s_nop 0
	global_store_dwordx2 v81, v[86:87], s[96:97]
	s_add_u32 s35, s71, 53
	v_readlane_b32 s96, v245, s35
	s_add_u32 s35, s35, 1
	v_readlane_b32 s97, v245, s35
	s_lshl_b32 s35, s32, 2
	s_nop 0
	s_add_u32 s96, s96, s35
	s_addc_u32 s97, s97, 0
	s_mov_b64 exec, 1
	global_store_dword v82, v88, s[96:97]
	s_mov_b64 exec, -1
	s_add_u32 s98, s98, s100
	s_min_u32 s32, s99, 0xffff
	s_lshr_b32 s71, s32, 15
	s_and_b32 s32, s32, 0x7fff
	s_lshl_b32 s71, s71, 1
	s_add_u32 s71, s71, 29
	v_readlane_b32 s96, v245, s71
	s_add_u32 s71, s71, 1
	v_readlane_b32 s97, v245, s71
	s_lshl_b32 s32, s32, 12
	s_nop 0
	s_add_u32 s96, s96, s32
	s_addc_u32 s97, s97, 0
	s_nop 0
	global_load_dwordx4 v[116:119], v80, s[96:97]
	global_load_dwordx4 v[120:123], v80, s[96:97] offset:16
	global_load_dwordx4 v[124:127], v80, s[96:97] offset:32
	global_load_dwordx4 v[128:131], v80, s[96:97] offset:48
	s_add_u32 s99, s99, s100
	s_cmp_ge_u32 s98, s101
	s_cbranch_scc1 .Luv_done
	s_waitcnt vmcnt(18)
	v_max3_f32 v84, |v160|, |v161|, 0
	v_max3_f32 v84, |v162|, |v163|, v84
	v_max3_f32 v84, |v164|, |v165|, v84
	v_max3_f32 v84, |v166|, |v167|, v84
	v_max3_f32 v84, |v168|, |v169|, v84
	v_max3_f32 v84, |v170|, |v171|, v84
	v_max3_f32 v84, |v172|, |v173|, v84
	v_max3_f32 v84, |v174|, |v175|, v84
	s_nop 1
	v_max_f32_dpp v84, v84, v84 quad_perm:[1,0,3,2] row_mask:0xf bank_mask:0xf
	s_nop 1
	v_max_f32_dpp v84, v84, v84 quad_perm:[2,3,0,1] row_mask:0xf bank_mask:0xf
	s_nop 1
	v_max_f32_dpp v84, v84, v84 row_half_mirror row_mask:0xf bank_mask:0xf
	s_nop 1
	v_max_f32_dpp v84, v84, v84 row_mirror row_mask:0xf bank_mask:0xf
	v_mov_b32_e32 v83, v84
	s_nop 1
	v_permlane16_swap_b32_e32 v84, v83
	v_max_f32_e32 v84, v84, v83
	v_mov_b32_e32 v83, v84
	s_nop 1
	v_permlane32_swap_b32_e32 v84, v83
	v_max_f32_e32 v84, v84, v83
	v_div_scale_f32 v90, s[96:97], v84, v84, s34
	v_rcp_f32_e32 v91, v90
	v_div_scale_f32 v92, vcc, s34, v84, s34
	v_fma_f32 v93, -v90, v91, 1.0
	v_fmac_f32_e32 v91, v93, v91
	v_mul_f32_e32 v93, v92, v91
	v_fma_f32 v94, -v90, v93, v92
	v_fmac_f32_e32 v93, v94, v91
	v_fma_f32 v92, -v90, v93, v92
	v_div_fmas_f32 v92, v92, v91, v93
	v_div_fixup_f32 v92, v92, v84, s34
	v_cmp_lt_f32_e32 vcc, 0, v84
	v_mov_b32_e32 v86, 0
	v_mov_b32_e32 v87, 0
	v_cndmask_b32_e32 v85, 1.0, v92, vcc
	v_mul_f32_e32 v160, v160, v85
	v_mul_f32_e32 v161, v161, v85
	v_mul_f32_e32 v162, v162, v85
	v_mul_f32_e32 v163, v163, v85
	v_mul_f32_e32 v164, v164, v85
	v_mul_f32_e32 v165, v165, v85
	v_mul_f32_e32 v166, v166, v85
	v_mul_f32_e32 v167, v167, v85
	v_mul_f32_e32 v168, v168, v85
	v_mul_f32_e32 v169, v169, v85
	v_mul_f32_e32 v170, v170, v85
	v_mul_f32_e32 v171, v171, v85
	v_mul_f32_e32 v172, v172, v85
	v_mul_f32_e32 v173, v173, v85
	v_mul_f32_e32 v174, v174, v85
	v_mul_f32_e32 v175, v175, v85
	v_cvt_scalef32_pk_fp4_f32 v86, v160, v161, 1.0
	v_cvt_scalef32_pk_fp4_f32 v87, v168, v169, 1.0
	v_cvt_scalef32_pk_fp4_f32 v86, v162, v163, 1.0 op_sel:[0,0,1,0]
	v_cvt_scalef32_pk_fp4_f32 v87, v170, v171, 1.0 op_sel:[0,0,1,0]
	v_cvt_scalef32_pk_fp4_f32 v86, v164, v165, 1.0 op_sel:[0,0,0,1]
	v_cvt_scalef32_pk_fp4_f32 v87, v172, v173, 1.0 op_sel:[0,0,0,1]
	v_cvt_scalef32_pk_fp4_f32 v86, v166, v167, 1.0 op_sel:[0,0,1,1]
	v_cvt_scalef32_pk_fp4_f32 v87, v174, v175, 1.0 op_sel:[0,0,1,1]
	v_mul_f32_e32 v88, 0x3e2aaaab, v84
	s_lshr_b32 s71, s98, 15
	s_and_b32 s32, s98, 0x7fff
	s_lshl_b32 s71, s71, 1
	s_add_u32 s35, s71, 45
	v_readlane_b32 s96, v245, s35
	s_add_u32 s35, s35, 1
	v_readlane_b32 s97, v245, s35
	s_lshl_b32 s35, s32, 9
	s_nop 0
	s_add_u32 s96, s96, s35
	s_addc_u32 s97, s97, 0
	s_nop 0
	global_store_dwordx2 v81, v[86:87], s[96:97]
	s_add_u32 s35, s71, 53
	v_readlane_b32 s96, v245, s35
	s_add_u32 s35, s35, 1
	v_readlane_b32 s97, v245, s35
	s_lshl_b32 s35, s32, 2
	s_nop 0
	s_add_u32 s96, s96, s35
	s_addc_u32 s97, s97, 0
	s_mov_b64 exec, 1
	global_store_dword v82, v88, s[96:97]
	s_mov_b64 exec, -1
	s_add_u32 s98, s98, s100
	s_min_u32 s32, s99, 0xffff
	s_lshr_b32 s71, s32, 15
	s_and_b32 s32, s32, 0x7fff
	s_lshl_b32 s71, s71, 1
	s_add_u32 s71, s71, 29
	v_readlane_b32 s96, v245, s71
	s_add_u32 s71, s71, 1
	v_readlane_b32 s97, v245, s71
	s_lshl_b32 s32, s32, 12
	s_nop 0
	s_add_u32 s96, s96, s32
	s_addc_u32 s97, s97, 0
	s_nop 0
	global_load_dwordx4 v[160:163], v80, s[96:97]
	global_load_dwordx4 v[164:167], v80, s[96:97] offset:16
	global_load_dwordx4 v[168:171], v80, s[96:97] offset:32
	global_load_dwordx4 v[172:175], v80, s[96:97] offset:48
	s_add_u32 s99, s99, s100
	s_cmp_ge_u32 s98, s101
	s_cbranch_scc1 .Luv_done
	s_waitcnt vmcnt(18)
	v_max3_f32 v84, |v176|, |v177|, 0
	v_max3_f32 v84, |v178|, |v179|, v84
	v_max3_f32 v84, |v180|, |v181|, v84
	v_max3_f32 v84, |v182|, |v183|, v84
	v_max3_f32 v84, |v184|, |v185|, v84
	v_max3_f32 v84, |v186|, |v187|, v84
	v_max3_f32 v84, |v188|, |v189|, v84
	v_max3_f32 v84, |v190|, |v191|, v84
	s_nop 1
	v_max_f32_dpp v84, v84, v84 quad_perm:[1,0,3,2] row_mask:0xf bank_mask:0xf
	s_nop 1
	v_max_f32_dpp v84, v84, v84 quad_perm:[2,3,0,1] row_mask:0xf bank_mask:0xf
	s_nop 1
	v_max_f32_dpp v84, v84, v84 row_half_mirror row_mask:0xf bank_mask:0xf
	s_nop 1
	v_max_f32_dpp v84, v84, v84 row_mirror row_mask:0xf bank_mask:0xf
	v_mov_b32_e32 v83, v84
	s_nop 1
	v_permlane16_swap_b32_e32 v84, v83
	v_max_f32_e32 v84, v84, v83
	v_mov_b32_e32 v83, v84
	s_nop 1
	v_permlane32_swap_b32_e32 v84, v83
	v_max_f32_e32 v84, v84, v83
	v_div_scale_f32 v90, s[96:97], v84, v84, s34
	v_rcp_f32_e32 v91, v90
	v_div_scale_f32 v92, vcc, s34, v84, s34
	v_fma_f32 v93, -v90, v91, 1.0
	v_fmac_f32_e32 v91, v93, v91
	v_mul_f32_e32 v93, v92, v91
	v_fma_f32 v94, -v90, v93, v92
	v_fmac_f32_e32 v93, v94, v91
	v_fma_f32 v92, -v90, v93, v92
	v_div_fmas_f32 v92, v92, v91, v93
	v_div_fixup_f32 v92, v92, v84, s34
	v_cmp_lt_f32_e32 vcc, 0, v84
	v_mov_b32_e32 v86, 0
	v_mov_b32_e32 v87, 0
	v_cndmask_b32_e32 v85, 1.0, v92, vcc
	v_mul_f32_e32 v176, v176, v85
	v_mul_f32_e32 v177, v177, v85
	v_mul_f32_e32 v178, v178, v85
	v_mul_f32_e32 v179, v179, v85
	v_mul_f32_e32 v180, v180, v85
	v_mul_f32_e32 v181, v181, v85
	v_mul_f32_e32 v182, v182, v85
	v_mul_f32_e32 v183, v183, v85
	v_mul_f32_e32 v184, v184, v85
	v_mul_f32_e32 v185, v185, v85
	v_mul_f32_e32 v186, v186, v85
	v_mul_f32_e32 v187, v187, v85
	v_mul_f32_e32 v188, v188, v85
	v_mul_f32_e32 v189, v189, v85
	v_mul_f32_e32 v190, v190, v85
	v_mul_f32_e32 v191, v191, v85
	v_cvt_scalef32_pk_fp4_f32 v86, v176, v177, 1.0
	v_cvt_scalef32_pk_fp4_f32 v87, v184, v185, 1.0
	v_cvt_scalef32_pk_fp4_f32 v86, v178, v179, 1.0 op_sel:[0,0,1,0]
	v_cvt_scalef32_pk_fp4_f32 v87, v186, v187, 1.0 op_sel:[0,0,1,0]
	v_cvt_scalef32_pk_fp4_f32 v86, v180, v181, 1.0 op_sel:[0,0,0,1]
	v_cvt_scalef32_pk_fp4_f32 v87, v188, v189, 1.0 op_sel:[0,0,0,1]
	v_cvt_scalef32_pk_fp4_f32 v86, v182, v183, 1.0 op_sel:[0,0,1,1]
	v_cvt_scalef32_pk_fp4_f32 v87, v190, v191, 1.0 op_sel:[0,0,1,1]
	v_mul_f32_e32 v88, 0x3e2aaaab, v84
	s_lshr_b32 s71, s98, 15
	s_and_b32 s32, s98, 0x7fff
	s_lshl_b32 s71, s71, 1
	s_add_u32 s35, s71, 45
	v_readlane_b32 s96, v245, s35
	s_add_u32 s35, s35, 1
	v_readlane_b32 s97, v245, s35
	s_lshl_b32 s35, s32, 9
	s_nop 0
	s_add_u32 s96, s96, s35
	s_addc_u32 s97, s97, 0
	s_nop 0
	global_store_dwordx2 v81, v[86:87], s[96:97]
	s_add_u32 s35, s71, 53
	v_readlane_b32 s96, v245, s35
	s_add_u32 s35, s35, 1
	v_readlane_b32 s97, v245, s35
	s_lshl_b32 s35, s32, 2
	s_nop 0
	s_add_u32 s96, s96, s35
	s_addc_u32 s97, s97, 0
	s_mov_b64 exec, 1
	global_store_dword v82, v88, s[96:97]
	s_mov_b64 exec, -1
	s_add_u32 s98, s98, s100
	s_min_u32 s32, s99, 0xffff
	s_lshr_b32 s71, s32, 15
	s_and_b32 s32, s32, 0x7fff
	s_lshl_b32 s71, s71, 1
	s_add_u32 s71, s71, 29
	v_readlane_b32 s96, v245, s71
	s_add_u32 s71, s71, 1
	v_readlane_b32 s97, v245, s71
	s_lshl_b32 s32, s32, 12
	s_nop 0
	s_add_u32 s96, s96, s32
	s_addc_u32 s97, s97, 0
	s_nop 0
	global_load_dwordx4 v[176:179], v80, s[96:97]
	global_load_dwordx4 v[180:183], v80, s[96:97] offset:16
	global_load_dwordx4 v[184:187], v80, s[96:97] offset:32
	global_load_dwordx4 v[188:191], v80, s[96:97] offset:48
	s_add_u32 s99, s99, s100
	s_branch .Luv_loop

.LBB0_44:
	s_andn2_b64 vcc, exec, s[6:7]
	s_cbranch_vccnz .LBB0_48
.LBB0_48:
	s_mov_b64 s[6:7], 0
